# v38 + attention phases: static s_setprio 1 for waves 4-7 (reset after the phase)
# speedup vs baseline: 1.0029x; 1.0029x over previous
; __device__ __forceinline__ void sw_attn(const bf16* QKV, const float* rope, const float* qg, const float* kg, const float* sinks, bf16* O, LAS unsigned char* lds, int tid) {
;     const int lane = tid & 63, wave = __builtin_amdgcn_readfirstlane(tid >> 6), l32 = lane & 31, hi = lane >> 5;
;     LAS unsigned char* kl = lds; LAS unsigned char* vl = lds + K_BYTES;
;     constexpr float QS = 0.125f * 1.4426950408889634f;
;     LAS float* gtab = (LAS float*)(lds + K_BYTES + V_BYTES);
;     if (tid < 64) { gtab[tid] = qg[tid]; gtab[64 + tid] = kg[tid]; }
;     for (int u = blockIdx.x; u < 512; u += gridDim.x) {
;         const int blk = u & 31, kvh = (u >> 5) & 1, b = u >> 6;
;     ...
;                 const bool live = !(blk == 0 && tb + js < 4);
;                 if (live) {
; #pragma unroll
;                     for (int ks = 0; ks < 4; ++ks) { const bf16x8 a = *(const LAS bf16x8*)(kl + (32 * (tb + js) + l32) * KROW + 32 * ks + 16 * hi); s[js] = SB_MFMA(a, qf[ks], s[js]); }
; #pragma unroll
;                     for (int r = 0; r < 16; ++r) {
;                         const int kk = (r & 3) + 8 * (r >> 2) + 4 * hi;
;                         float v = s[js][r];
;                         if (js == 0) v = (kk > l32) ? v : NEG;
;                         if (js == 4) v = (kk <= l32) ? v : NEG;
;                         s[js][r] = v; mx = fmaxf(mx, v);
;                     }
;                 } else {
; #pragma unroll
;                     for (int r = 0; r < 16; ++r) s[js][r] = NEG;
;                 }
;                 asm volatile("" ::: "memory");
;             }
;             { float lo_, up_; halves(mx, lo_, up_); mx = fmaxf(lo_, up_); }
;             float l = 0.f;
;             f32x16 o0, o1;
; #pragma unroll
;             for (int r = 0; r < 16; ++r) { o0[r] = 0.f; o1[r] = 0.f; }
; #pragma unroll
;             for (int js = 0; js < 5; ++js) {
;                 unsigned pw[8];
; #pragma unroll
;                 for (int r = 0; r < 16; r += 2) { const float p0 = __builtin_amdgcn_exp2f(s[js][r] - mx), p1 = __builtin_amdgcn_exp2f(s[js][r + 1] - mx); l += p0 + p1; pw[r >> 1] = cvtpk(p0, p1); }
; #pragma unroll
;                 for (int kk = 0; kk < 2; ++kk) {
;                     const v4u pv = {pw[4 * kk], pw[4 * kk + 1], pw[4 * kk + 2], pw[4 * kk + 3]};
;                     const bf16x8 pb = __builtin_bit_cast(bf16x8, pv);
; #pragma unroll
.LBB0_156:
	s_or_b64 exec, exec, s[6:7]
	v_readlane_b32 s6, v254, 15
	v_readlane_b32 s7, v254, 16
	s_andn2_b64 vcc, exec, s[6:7]
	s_cbranch_vccnz .LBB0_188
	s_lshl_b32 s6, s98, 4
	s_ashr_i32 s7, s6, 31
	s_lshl_b64 s[6:7], s[6:7], 2
	v_readlane_b32 s9, v253, 4
	s_waitcnt lgkmcnt(0)
	v_bfe_u32 v7, v168, 5, 1
	s_add_u32 s27, s9, s6
	v_readlane_b32 s6, v253, 5
	v_lshlrev_b32_e32 v0, 4, v7
	v_mov_b32_e32 v1, v157
	s_addc_u32 s88, s6, s7
	v_lshl_add_u64 v[112:113], s[90:91], 0, v[0:1]
	v_and_b32_e32 v1, 1, v168
	v_readlane_b32 s6, v254, 29
	v_and_b32_e32 v3, 63, v168
	v_ashrrev_i32_e32 v119, 1, v168
	v_lshl_add_u32 v129, v1, 7, s6
	v_cmp_eq_u32_e64 s[6:7], 0, v1
	v_lshlrev_b32_e32 v4, 2, v3
	v_xor_b32_e32 v121, 4, v4
	v_writelane_b32 v252, s6, 0
	v_mov_b32_e32 v5, v157
	v_cmp_gt_u32_e64 s[40:41], 32, v3
	v_writelane_b32 v252, s7, 1
	s_movk_i32 s6, 0x90
	v_mul_lo_u32 v4, v119, s6
	v_add_u32_e32 v8, 0, v4
	v_lshlrev_b32_e32 v4, 3, v168
	v_and_b32_e32 v9, 56, v4
	v_lshlrev_b32_e32 v4, 1, v9
	v_lshl_add_u64 v[114:115], s[90:91], 0, v[4:5]
	v_and_b32_e32 v5, 32, v168
	s_add_i32 s6, 0, 0x11200
	v_add_u32_e32 v131, s6, v5
	v_lshlrev_b32_e32 v3, 2, v7
	s_movk_i32 s6, 0x208
	v_and_b32_e32 v6, 31, v168
	v_lshlrev_b32_e32 v156, 3, v7
	v_mad_u32_u24 v7, v9, s6, 0
	v_or_b32_e32 v9, 2, v3
	v_cmp_gt_u32_e64 s[46:47], v9, v6
	v_or_b32_e32 v9, 3, v3
	v_cmp_gt_u32_e64 s[48:49], v9, v6
	v_or_b32_e32 v9, 8, v3
	v_cmp_gt_u32_e64 s[50:51], v9, v6
	v_or_b32_e32 v9, 9, v3
	v_cmp_gt_u32_e64 s[52:53], v9, v6
	v_or_b32_e32 v9, 10, v3
	s_ashr_i32 s99, s8, 6
	v_cmp_gt_u32_e64 s[54:55], v9, v6
	v_or_b32_e32 v9, 11, v3
	s_lshl_b32 s6, s99, 5
	s_and_b32 s10, s99, 3
	v_cmp_gt_u32_e64 s[56:57], v9, v6
	v_or_b32_e32 v9, 16, v3
	s_ashr_i32 s28, s8, 8
	s_and_b32 s6, s6, 0x60
	s_add_i32 s11, s10, 1
	v_cmp_gt_u32_e64 s[58:59], v9, v6
	v_or_b32_e32 v9, 17, v3
	s_cmp_eq_u32 s10, 3
	v_cmp_gt_u32_e64 s[60:61], v9, v6
	v_or_b32_e32 v9, 18, v3
	s_cselect_b64 s[38:39], -1, 0
	s_add_i32 s12, s10, 2
	v_cmp_gt_u32_e64 s[62:63], v9, v6
	v_or_b32_e32 v9, 19, v3
	s_cmp_gt_u32 s10, 1
	v_cmp_gt_u32_e64 s[64:65], v9, v6
	v_or_b32_e32 v9, 24, v3
	v_or_b32_e32 v118, s6, v6
	s_cselect_b64 s[6:7], -1, 0
	s_add_i32 s13, s10, 3
	v_cmp_gt_u32_e64 s[66:67], v9, v6
	v_or_b32_e32 v9, 25, v3
	s_cmp_lg_u32 s10, 0
	v_add_u32_e32 v0, 0, v0
	v_cmp_gt_u32_e64 s[42:43], v3, v6
	v_cmp_lt_u32_e64 s[44:45], v3, v6
	v_cmp_gt_u32_e64 s[68:69], v9, v6
	v_or_b32_e32 v9, 26, v3
	v_or_b32_e32 v3, 27, v3
	s_cselect_b64 s[8:9], -1, 0
	s_or_b32 s14, s10, 4
	v_sub_u32_e32 v5, v0, v156
	v_cmp_gt_u32_e64 s[70:71], v9, v6
	v_cmp_gt_u32_e64 s[72:73], v3, v6
	v_mul_u32_u24_e32 v3, 0x208, v6
	v_lshl_or_b32 v120, s10, 5, v6
	v_lshl_or_b32 v10, s11, 5, v6
	v_lshl_or_b32 v11, s12, 5, v6
	v_lshl_or_b32 v12, s13, 5, v6
	v_lshl_or_b32 v6, s14, 5, v6
	v_lshlrev_b32_e32 v2, 5, v1
	v_lshlrev_b32_e32 v1, 6, v1
	v_and_b32_e32 v4, -8, v168
	v_mul_u32_u24_e32 v9, 0x90, v120
	v_mul_u32_u24_e32 v10, 0x90, v10
	v_mul_u32_u24_e32 v11, 0x90, v11
	v_mul_u32_u24_e32 v12, 0x90, v12
	v_mul_u32_u24_e32 v6, 0x90, v6
	v_lshl_add_u32 v13, s10, 6, v5
	v_lshl_add_u32 v14, s11, 6, v5
	v_lshl_add_u32 v15, s12, 6, v5
	v_lshl_add_u32 v16, s13, 6, v5
	v_lshl_add_u32 v5, s14, 6, v5
	v_and_b32_e32 v130, -4, v119
	v_lshl_add_u64 v[116:117], s[92:93], 0, v[156:157]
	v_lshlrev_b32_e32 v122, 1, v2
	v_add_u32_e32 v132, v8, v1
	v_add_u32_e32 v133, v7, v4
	v_add_u32_e32 v134, v0, v9
	v_add_u32_e32 v135, v0, v10
	v_add_u32_e32 v136, v0, v11
	v_add_u32_e32 v137, v0, v12
	v_add_u32_e32 v138, v0, v6
	v_add_u32_e32 v139, v13, v3
	v_add_u32_e32 v140, v14, v3
	v_add_u32_e32 v141, v15, v3
	v_add_u32_e32 v142, v16, v3
	v_add_u32_e32 v143, v5, v3
	s_mov_b32 s29, s2
	s_and_b32 s14, s99, 4
	s_cmp_eq_u32 s14, 0
	s_cbranch_scc1 .Lsw_pr
	s_setprio 1
.Lsw_pr:
	s_branch .LBB0_159
.LBB0_158:
	s_add_i32 s29, s29, s82
	s_cmpk_gt_i32 s29, 0x1ff
	s_cbranch_scc1 .LBB0_188

; #define LAS __attribute__((address_space(3)))
; __device__ __forceinline__ void sb_attn(const bf16* QKV, bf16* O, LAS unsigned char* lds, int tid) {
;     const int lane = tid & 63, wave = __builtin_amdgcn_readfirstlane(tid >> 6), l32 = lane & 31, hi = lane >> 5;
;     const int vdc = lane & 7, vkg = lane >> 3;
;     LAS unsigned char* vimg = lds + wave * WV_BYTES; LAS unsigned char* kimg = vimg + WV_BUF;
;     const int gw = blockIdx.x * NWAVES + wave, NGW = gridDim.x * NWAVES;
;     for (int u = gw; u < BATCH * 16 * (SEQ / 32); u += NGW) {
.LBB0_189:
	s_and_b64 vcc, exec, s[6:7]
	s_cbranch_vccz .LBB0_200
	v_readfirstlane_b32 s7, v168
	s_ashr_i32 s6, s7, 6
	v_readlane_b32 s8, v253, 8
	s_add_i32 s8, s6, s8
	s_cmpk_gt_i32 s8, 0x3fff
	s_cbranch_scc1 .LBB0_200
	s_and_b32 s14, s6, 4
	s_cmp_eq_u32 s14, 0
	s_cbranch_scc1 .Lsb_pr
	s_setprio 1

; __global__ void __launch_bounds__(NTHR, 2) fwd_megakernel(Args a) {
;     ...
;                 if (sb) { for (int rep = 0; rep < RPT_SB; ++rep) sbat::sb_attn(QKV, OB, ldsl, tid); }
;                 else for (int rep = 0; rep < RPT_SW; ++rep) swat::sw_attn(QKV, rope, small + slot * HD, small + 128 + slot * HD, small + 256 + slot * 16, OB, ldsl, tid);
;     ...
;         if (ph + 1 < ph1) { for (int rep = 0; rep < RPT_SYNC; ++rep) xcd_barrier(bar); }
.LBB0_200:
	s_setprio 0
	s_mov_b64 s[6:7], 0
